# dn_scan: the two halves share one LDS copy of the W/IN/Q/K^T tiles (half 0 loads W,IN; half 1 Q,K): half the operand loads and staging writes
# speedup vs baseline: 1.0158x; 1.0032x over previous
.LBB0_1377:
	s_or_b64 exec, exec, s[10:11]
	s_and_b64 s[8:9], s[2:3], exec
	s_cselect_b32 s9, s60, s62
	v_readlane_b32 s10, v254, 23
	s_cselect_b32 s8, s61, s63
	v_and_b32_e32 v50, 15, v39
	v_lshrrev_b32_e32 v52, 2, v39
	v_readlane_b32 s11, v254, 24
	s_add_u32 s9, s9, s10
	v_bfe_u32 v37, v39, 4, 2
	v_mul_u32_u24_e32 v51, 0x48, v50
	v_and_b32_e32 v52, 48, v52
	s_addc_u32 s10, s8, 0
	s_lshl_b32 s11, s19, 5
	v_lshl_add_u32 v51, v51, 1, s33
	v_lshlrev_b32_e32 v53, 1, v52
	v_lshlrev_b32_e32 v54, 2, v37
	v_lshlrev_b32_e32 v55, 3, v37
	v_lshlrev_b32_e32 v37, 4, v37
	s_add_u32 s8, s9, s11
	v_add3_u32 v86, v51, v53, v55
	v_or_b32_e32 v53, v52, v50
	v_add_u32_e32 v83, v51, v37
	s_addc_u32 s9, s10, 0
	v_lshlrev_b32_e32 v50, 1, v50
	v_mov_b32_e32 v51, v129
	v_lshl_add_u64 v[60:61], s[8:9], 0, v[50:51]
	v_and_b32_e32 v104, 0xff, v131
	v_lshrrev_b32_e32 v104, 1, v104
	v_lshlrev_b32_e32 v104, 9, v104
	v_and_b32_e32 v105, 1, v131
	v_lshl_or_b32 v104, v105, 4, v104
	v_mov_b32_e32 v105, 0
	v_lshl_add_u64 v[104:105], s[8:9], 0, v[104:105]
	v_lshrrev_b32_e32 v51, 1, v42
	v_mul_u32_u24_e32 v51, 48, v51
	v_lshl_add_u32 v49, v49, 1, s33
	v_add3_u32 v96, s33, v51, v36
	v_mul_u32_u24_e32 v36, 0x48, v44
	v_lshl_add_u32 v100, v36, 1, v49
	v_mul_u32_u24_e32 v36, 0x48, v45
	v_lshlrev_b32_e32 v36, 1, v36
	v_lshlrev_b32_e32 v43, 1, v43
	v_mul_u32_u24_e32 v53, 0x48, v53
	v_add3_u32 v99, s33, v36, v43
	v_mul_u32_u24_e32 v36, 0x48, v46
	v_lshlrev_b32_e32 v53, 1, v53
	v_lshl_add_u32 v98, v36, 1, v49
	v_mul_u32_u24_e32 v36, 0x48, v48
	v_add3_u32 v82, s33, v53, v37
	v_or_b32_e32 v37, v54, v52
	v_lshlrev_b32_e32 v36, 1, v36
	v_bitop3_b32 v48, v54, 63, v52 bitop3:0x36
	v_lshl_add_u32 v84, v37, 2, s33
	v_add3_u32 v97, s33, v36, v43
	v_mad_u32_u24 v43, v37, 48, s33
	v_or_b32_e32 v36, 1, v37
	v_mul_i32_i24_e32 v44, 0xffffffd4, v37
	v_or_b32_e32 v45, 2, v37
	v_or_b32_e32 v46, 3, v37
	v_cndmask_b32_e64 v85, v48, v37, s[2:3]
	v_bitop3_b32 v37, v54, 62, v52 bitop3:0x36
	v_cndmask_b32_e64 v81, v37, v36, s[2:3]
	v_bitop3_b32 v36, v54, 61, v52 bitop3:0x36
	v_cndmask_b32_e64 v80, v36, v45, s[2:3]
	v_bitop3_b32 v36, v54, 60, v52 bitop3:0x36
	v_cndmask_b32_e64 v78, v36, v46, s[2:3]
	v_and_b32_e32 v36, 0x1f80, v47
	v_and_b32_e32 v37, 1, v39
	v_or_b32_e32 v36, s13, v36
	v_lshlrev_b32_e32 v37, 4, v37
	v_readlane_b32 s8, v254, 11
	v_or3_b32 v36, v36, s11, v37
	v_mov_b32_e32 v37, s17
	v_readlane_b32 s9, v254, 12
	v_mov_b32_e32 v39, v129
	v_add_u32_e32 v95, s33, v38
	v_lshl_add_u64 v[70:71], s[8:9], 0, v[36:37]
	v_readlane_b32 s8, v254, 13
	v_add_u32_e32 v93, v43, v50
	v_lshl_add_u64 v[38:39], v[40:41], 0, v[38:39]
	v_readlane_b32 s9, v254, 14
	v_lshl_or_b32 v36, v42, 4, s13
	s_lshl_b32 s16, s16, 12
	v_add_u32_e32 v92, 48, v93
	v_add_u32_e32 v89, 0x60, v93
	v_add_u32_e32 v87, 0x90, v93
	v_lshl_add_u64 v[72:73], s[8:9], 0, v[38:39]
	v_lshl_add_u64 v[74:75], s[52:53], 0, v[36:37]
	v_lshl_add_u64 v[76:77], s[56:57], 0, v[36:37]
	s_movk_i32 s17, 0x42
	s_mov_b32 s19, -3
	s_mov_b64 s[8:9], 0
	v_add_u32_e32 v79, v43, v44
	v_mov_b32_e32 v67, v66
	v_mov_b32_e32 v68, v66
	v_mov_b32_e32 v69, v66
	v_and_b32_e32 v204, 15, v131
	v_lshlrev_b32_e32 v204, 1, v204
	v_add_u32_e32 v204, 0xc000, v204
	v_add_u32_e32 v204, s33, v204
	v_lshl_add_u32 v107, v85, 5, v204
	v_lshl_add_u32 v112, v81, 5, v204
	v_lshl_add_u32 v133, v80, 5, v204
	v_lshl_add_u32 v188, v78, 5, v204
	v_and_b32_e32 v204, 0xff, v131
	v_lshlrev_b32_e32 v204, 4, v204
	v_add_u32_e32 v204, 0xc000, v204
	v_add_u32_e32 v204, s33, v204
	v_readfirstlane_b32 s25, v131
	s_nop 0
	s_lshr_b32 s25, s25, 8
	s_and_b32 s25, s25, 1
	s_lshl_b32 s26, s25, 16
	s_nop 0
	v_subrev_u32_e32 v82, s26, v82
	v_subrev_u32_e32 v97, s26, v97
	v_subrev_u32_e32 v98, s26, v98
	v_subrev_u32_e32 v99, s26, v99
	v_subrev_u32_e32 v100, s26, v100
.LBB0_1378:
	s_barrier
	s_waitcnt vmcnt(0)
	s_cmp_eq_u32 s25, 0
	s_cbranch_scc0 .Lscan_st1
	ds_write_b128 v100, v[4:7]
	ds_write_b128 v100, v[8:11] offset:9216
	ds_write_b128 v98, v[16:19]
	ds_write_b128 v98, v[20:23] offset:9216
	s_branch .Lscan_std
.Lscan_st1:
	ds_write_b128 v100, v[24:27] offset:18432
	ds_write_b16 v99, v12 offset:27648
	ds_write_b16_d16_hi v99, v12 offset:27792
	ds_write_b16 v99, v13 offset:27936
	ds_write_b16_d16_hi v99, v13 offset:28080
	ds_write_b16 v99, v14 offset:28224
	ds_write_b16_d16_hi v99, v14 offset:28368
	ds_write_b16 v99, v15 offset:28512
	ds_write_b16_d16_hi v99, v15 offset:28656
	ds_write_b128 v98, v[32:35] offset:18432
	ds_write_b16 v97, v28 offset:27648
	ds_write_b16_d16_hi v97, v28 offset:27792
	ds_write_b16 v97, v29 offset:27936
	ds_write_b16_d16_hi v97, v29 offset:28080
	ds_write_b16 v97, v30 offset:28224
	ds_write_b16_d16_hi v97, v30 offset:28368
	ds_write_b16 v97, v31 offset:28512
	ds_write_b16_d16_hi v97, v31 offset:28656
.Lscan_std:
	s_and_saveexec_b64 s[10:11], s[4:5]
	ds_write_b128 v96, v[0:3] offset:36864
	s_or_b64 exec, exec, s[10:11]
	s_and_saveexec_b64 s[10:11], s[6:7]
	ds_write_b32 v95, v94 offset:46848
	s_or_b64 exec, exec, s[10:11]
	v_cvt_pk_bf16_f32 v4, v66, v67
	v_cvt_pk_bf16_f32 v5, v68, v69
	ds_write_b64 v86, v[4:5] offset:39936
	s_cmp_gt_i32 s19, -3
	s_cbranch_scc0 .Lscan_nofl
	s_and_saveexec_b64 s[10:11], s[4:5]
	ds_read_b128 v[36:39], v204
	s_lshl_b32 s26, s24, 9
	s_mov_b32 s27, 0
	v_lshl_add_u64 v[150:151], v[104:105], 0, s[26:27]
	s_waitcnt lgkmcnt(0)
	global_store_dwordx4 v[150:151], v[36:39], off
	s_or_b64 exec, exec, s[10:11]

.LBB0_1386:
	s_lshl_b32 s13, s13, 6
	s_add_i32 s13, s13, s10
	v_add_u32_e32 v6, s13, v88
	v_mov_b64_e32 v[4:5], s[0:1]
	s_movk_i32 s20, 0x600
	v_lshl_add_u64 v[16:17], v[74:75], 0, s[8:9]
	v_mad_i64_i32 v[28:29], s[10:11], v6, s20, v[4:5]
	v_add_co_u32_e32 v4, vcc, 0x2000, v16
	v_lshl_add_u64 v[20:21], v[76:77], 0, s[8:9]
	s_nop 0
	v_addc_co_u32_e32 v5, vcc, 0, v17, vcc
	v_add_co_u32_e32 v8, vcc, 0x2000, v20
	v_add_u32_e32 v12, s13, v90
	s_nop 0
	v_addc_co_u32_e32 v9, vcc, 0, v21, vcc
	v_add_co_u32_e32 v16, vcc, 0x3000, v16
	v_add_u32_e32 v30, s13, v91
	s_nop 0
	v_addc_co_u32_e32 v17, vcc, 0, v17, vcc
	v_add_co_u32_e32 v20, vcc, 0x3000, v20
	v_mov_b32_e32 v65, v129
	v_mad_i64_i32 v[12:13], s[10:11], v12, s20, v[62:63]
	v_lshl_add_u64 v[14:15], v[28:29], 0, v[128:129]
	v_addc_co_u32_e32 v21, vcc, 0, v21, vcc
	v_mad_i64_i32 v[30:31], s[10:11], v30, s20, v[62:63]
	v_lshl_add_u64 v[28:29], v[28:29], 0, v[64:65]
	s_cmp_eq_u32 s25, 0
	s_cbranch_scc0 .Lscan_ld1
	global_load_dwordx4 v[4:7], v[4:5], off
	s_nop 0
	global_load_dwordx4 v[8:11], v[8:9], off
	s_nop 0
	global_load_dwordx4 v[16:19], v[16:17], off
	s_nop 0
	global_load_dwordx4 v[20:23], v[20:21], off
	s_branch .Lscan_ldd
.Lscan_ld1:
	global_load_dwordx4 v[24:27], v[12:13], off
	s_nop 0
	global_load_dwordx4 v[12:15], v[14:15], off offset:512
	s_nop 0
	global_load_dwordx4 v[32:35], v[30:31], off
	s_nop 0
	global_load_dwordx4 v[28:31], v[28:29], off offset:512
.Lscan_ldd:
	s_and_saveexec_b64 s[10:11], s[4:5]
	s_cbranch_execz .LBB0_1388
	v_lshl_add_u64 v[0:1], v[70:71], 0, s[8:9]
	global_load_dwordx4 v[0:3], v[0:1], off
